# prompt MLA loop: next-tile V loads and K-DMA address prep issued before the loop barrier (where the wave parks), only the 3 DMA issues remain after it
# baseline (speedup 1.0000x reference)
.LBB0_556:
	s_waitcnt vmcnt(0)
	ds_write2_b64 v192, v[168:169], v[170:171] offset1:1
	ds_write2_b64 v193, v[164:165], v[166:167] offset1:1
	s_cmp_ge_u32 s58, s27
	s_cbranch_scc1 .Lt_last
	v_readlane_b32 s12, v253, 29
	v_readlane_b32 s13, v253, 30
	s_nop 3
	s_lshl_b64 s[12:13], s[12:13], 1
	s_nop 0
	v_lshl_add_u64 v[158:159], v[172:173], 0, s[12:13]
	v_lshl_add_u64 v[160:161], v[174:175], 0, s[12:13]
	global_load_dwordx4 v[168:171], v[158:159], off
	global_load_dwordx4 v[164:167], v[160:161], off
	v_readfirstlane_b32 s12, v152
	v_readfirstlane_b32 s13, v153
	v_readlane_b32 s22, v253, 29
	s_nop 3
	s_mul_i32 s23, s22, 0x140
	s_add_u32 s12, s12, s23
	s_addc_u32 s13, s13, 0
	s_xor_b32 s23, s98, 0x10000
	s_add_i32 s23, s23, s99
	s_waitcnt lgkmcnt(0)
	s_barrier
	ds_read_b128 v[196:199], v188
	ds_read_b128 v[202:205], v188 offset:32
	ds_read_b128 v[206:209], v188 offset:64
	ds_read_b128 v[210:213], v188 offset:96
	ds_read_b128 v[220:223], v188 offset:128
	ds_read_b128 v[224:227], v188 offset:160
	ds_read_b128 v[2:5], v188 offset:192
	ds_read_b128 v[6:9], v188 offset:224
	s_mov_b32 m0, s23
	s_nop 0
	global_load_lds_dwordx4 v154, s[12:13]
	s_add_i32 m0, s23, 0x2000
	s_nop 0
	global_load_lds_dwordx4 v155, s[12:13]
	s_cmp_ge_u32 s99, 0x1400
	s_cbranch_scc1 .LBB0_566
	s_add_i32 m0, s23, 0x4000
	s_nop 0
	global_load_lds_dwordx4 v156, s[12:13]
	s_branch .LBB0_566
.Lt_last:
	s_waitcnt lgkmcnt(0)
	s_barrier
	ds_read_b128 v[196:199], v188
	ds_read_b128 v[202:205], v188 offset:32
	ds_read_b128 v[206:209], v188 offset:64
	ds_read_b128 v[210:213], v188 offset:96
	ds_read_b128 v[220:223], v188 offset:128
	ds_read_b128 v[224:227], v188 offset:160
	ds_read_b128 v[2:5], v188 offset:192
	ds_read_b128 v[6:9], v188 offset:224
